# touch-prefetch of epilogue residual tile (P5 x at K-iter 20, P8 out at K-iter 116) from inside the K loop
# baseline (speedup 1.0000x reference)
;     __device__ __forceinline__ void operator()(const f32x4 (&acc)[2][2][4][2], const Unit& u, int wr, int wc, int fr, int fq) const {
;     ...
;             for (int m = 0; m < 4; ++m) { const int row = row0 + ai * HALF + m * 16; const size_t off = (size_t)row * 2048 + col0; float ss = 0.f;
; #pragma unroll
;                 for (int bj = 0; bj < 2; ++bj)
; #pragma unroll
;                     for (int n = 0; n < 2; ++n) { const f32x4 bs = __builtin_nontemporal_load((const f32x4*)(base + off + bj * HALF + n * 16)); const f32x4 x1 = bs + gv[bj][n] * acc[ai][bj][m][n];
; template <class Epi, class Sched, bool ALIGN_EPI = false, bool SP2 = false>
; __device__ __forceinline__ void gemm_phase(PG8_LAS unsigned char* lds, const Gemm g, const Sched& S, const Epi& E) {
;     ...
;         for (int t = 0; t < nt; t += 2) {
;             const bool last = (t == nt - 2);
.LBB0_894:
	s_cmp_lg_u32 s58, 20
	s_cbranch_scc1 .Lpf_skip_p5
	v_readlane_b32 s98, v236, 7
	v_readlane_b32 s99, v236, 8
	v_and_b32_e32 v237, 12, v168
	v_lshl_add_u32 v237, v237, 2, v166
	v_lshl_add_u32 v237, s36, 8, v237
	v_and_b32_e32 v238, 0xe0, v168
	v_lshl_or_b32 v238, s34, 8, v238
	v_lshlrev_b32_e32 v238, 2, v238
	v_lshl_add_u32 v237, v237, 13, v238
	global_load_dword v238, v237, s[98:99]
	global_load_dword v238, v237, s[98:99] offset:512
	v_add_u32_e32 v237, 0x100000, v237
	global_load_dword v238, v237, s[98:99]
	global_load_dword v238, v237, s[98:99] offset:512

;     __device__ __forceinline__ void operator()(const f32x4 (&acc)[2][2][4][2], const Unit& u, int wr, int wc, int fr, int fq) const {
;     ...
;             for (int m = 0; m < 4; ++m) { const size_t off = (size_t)(row0 + ai * HALF + m * 16) * 2048 + col0;
; #pragma unroll
;                 for (int bj = 0; bj < 2; ++bj)
; #pragma unroll
;                     for (int n = 0; n < 2; ++n) { const f32x4 bs = __builtin_nontemporal_load((const f32x4*)(base + off + bj * HALF + n * 16));
; template <class Epi, class Sched, bool ALIGN_EPI = false, bool SP2 = false>
; __device__ __forceinline__ void gemm_phase(PG8_LAS unsigned char* lds, const Gemm g, const Sched& S, const Epi& E) {
;     ...
;         for (int t = 0; t < nt; t += 2) {
;             const bool last = (t == nt - 2);
.LBB0_1071:
	s_cmp_lg_u32 s55, 116
	s_cbranch_scc1 .Lpf_skip_p8
	v_and_b32_e32 v237, 12, v164
	v_lshl_add_u32 v237, v237, 2, v162
	v_lshl_add_u32 v237, s24, 8, v237
	v_and_b32_e32 v238, 0xe0, v164
	v_lshl_or_b32 v238, s25, 8, v238
	v_lshlrev_b32_e32 v238, 2, v238
	v_lshl_add_u32 v237, v237, 13, v238
	global_load_dword v238, v237, s[66:67]
	global_load_dword v238, v237, s[66:67] offset:512
	v_add_u32_e32 v237, 0x100000, v237
	global_load_dword v238, v237, s[66:67]
	global_load_dword v238, v237, s[66:67] offset:512

; #define LAS __attribute__((address_space(3)))
; __global__ void __launch_bounds__(NTHR, 2) fwd_megakernel(Args a) {
;     extern __shared__ __attribute__((aligned(16))) unsigned char lds_raw[];
;     cg::grid_group grid = cg::this_grid();
;     LAS unsigned char* lds = (LAS unsigned char*)lds_raw;
;     const int tid = threadIdx.x, lane = tid & 63, wave = __builtin_amdgcn_readfirstlane(tid >> 6);
;     const int G = gridDim.x, blk = blockIdx.x;
;     const int vcu = (G % 8 == 0) ? (blk % 8) * (G / 8) + blk / 8 : blk;
;     const int gw = vcu * 8 + wave, NGW = G * 8;
	.amdhsa_kernel _Z14fwd_megakernel4Args
		.amdhsa_group_segment_fixed_size 0
		.amdhsa_private_segment_fixed_size 0
		.amdhsa_kernarg_size 408
		.amdhsa_user_sgpr_count 2
		.amdhsa_user_sgpr_dispatch_ptr 0
		.amdhsa_user_sgpr_queue_ptr 0
		.amdhsa_user_sgpr_kernarg_segment_ptr 1
		.amdhsa_user_sgpr_dispatch_id 0
		.amdhsa_user_sgpr_kernarg_preload_length 0
		.amdhsa_user_sgpr_kernarg_preload_offset 0
		.amdhsa_user_sgpr_private_segment_size 0
		.amdhsa_uses_dynamic_stack 0
		.amdhsa_enable_private_segment 0
		.amdhsa_system_sgpr_workgroup_id_x 1
		.amdhsa_system_sgpr_workgroup_id_y 0
		.amdhsa_system_sgpr_workgroup_id_z 0
		.amdhsa_system_sgpr_workgroup_info 0
		.amdhsa_system_vgpr_workitem_id 2
		.amdhsa_next_free_vgpr 239
		.amdhsa_next_free_sgpr 102
		.amdhsa_accum_offset 240
		.amdhsa_reserve_vcc 1
		.amdhsa_float_round_mode_32 0
		.amdhsa_float_round_mode_16_64 0
		.amdhsa_float_denorm_mode_32 3
		.amdhsa_float_denorm_mode_16_64 3
		.amdhsa_dx10_clamp 1
		.amdhsa_ieee_mode 1
		.amdhsa_fp16_overflow 0
		.amdhsa_tg_split 0
		.amdhsa_exception_fp_ieee_invalid_op 0
		.amdhsa_exception_fp_denorm_src 0
		.amdhsa_exception_fp_ieee_div_zero 0
		.amdhsa_exception_fp_ieee_overflow 0
		.amdhsa_exception_fp_ieee_underflow 0
		.amdhsa_exception_fp_ieee_inexact 0
		.amdhsa_exception_int_div_zero 0
	.end_amdhsa_kernel

; #define LAS __attribute__((address_space(3)))
; __global__ void __launch_bounds__(NTHR, 2) fwd_megakernel(Args a) {
;     extern __shared__ __attribute__((aligned(16))) unsigned char lds_raw[];
;     cg::grid_group grid = cg::this_grid();
;     LAS unsigned char* lds = (LAS unsigned char*)lds_raw;
;     const int tid = threadIdx.x, lane = tid & 63, wave = __builtin_amdgcn_readfirstlane(tid >> 6);
;     const int G = gridDim.x, blk = blockIdx.x;
;     const int vcu = (G % 8 == 0) ? (blk % 8) * (G / 8) + blk / 8 : blk;
;     const int gw = vcu * 8 + wave, NGW = G * 8;
amdhsa.kernels:
  - .agpr_count:     0
    .args:
      - .offset:         0
        .size:           152
        .value_kind:     by_value
      - .offset:         152
        .size:           4
        .value_kind:     hidden_block_count_x
      - .offset:         156
        .size:           4
        .value_kind:     hidden_block_count_y
      - .offset:         160
        .size:           4
        .value_kind:     hidden_block_count_z
      - .offset:         164
        .size:           2
        .value_kind:     hidden_group_size_x
      - .offset:         166
        .size:           2
        .value_kind:     hidden_group_size_y
      - .offset:         168
        .size:           2
        .value_kind:     hidden_group_size_z
      - .offset:         170
        .size:           2
        .value_kind:     hidden_remainder_x
      - .offset:         172
        .size:           2
        .value_kind:     hidden_remainder_y
      - .offset:         174
        .size:           2
        .value_kind:     hidden_remainder_z
      - .offset:         192
        .size:           8
        .value_kind:     hidden_global_offset_x
      - .offset:         200
        .size:           8
        .value_kind:     hidden_global_offset_y
      - .offset:         208
        .size:           8
        .value_kind:     hidden_global_offset_z
      - .offset:         216
        .size:           2
        .value_kind:     hidden_grid_dims
      - .offset:         240
        .size:           8
        .value_kind:     hidden_multigrid_sync_arg
      - .offset:         272
        .size:           4
        .value_kind:     hidden_dynamic_lds_size
    .group_segment_fixed_size: 0
    .kernarg_segment_align: 8
    .kernarg_segment_size: 408
    .language:       OpenCL C
    .language_version:
      - 2
      - 0
    .max_flat_workgroup_size: 512
    .name:           _Z14fwd_megakernel4Args
    .private_segment_fixed_size: 0
    .sgpr_count:     108
    .sgpr_spill_count: 83
    .symbol:         _Z14fwd_megakernel4Args.kd
    .uniform_work_group_size: 1
    .uses_dynamic_stack: false
    .vgpr_count:     239
    .vgpr_spill_count: 0
    .wavefront_size: 64
